# attention loop: K/V stage DMA issued at different points of the PV section by the comp-0 and comp-1 waves (staggered TA pressure)
# baseline (speedup 1.0000x reference)
.LBB0_1328:
.LBB0_1329:
	s_waitcnt lgkmcnt(1)
	v_mfma_f32_16x16x32_bf16 v[168:171], v[78:81], v[18:21], v[90:93]
	ds_read_b128 v[78:81], v131 offset:57344
	s_waitcnt lgkmcnt(1)
	v_mfma_f32_16x16x32_bf16 v[172:175], v[86:89], v[18:21], v[94:97]
	ds_read_b128 v[86:89], v131 offset:59392
	v_exp_f32_e32 v145, v74
	v_exp_f32_e32 v146, v75
	v_exp_f32_e32 v147, v76
	v_exp_f32_e32 v148, v77
	ds_read_b128 v[176:179], v131 offset:61440
	s_waitcnt lgkmcnt(2)
	v_mfma_f32_16x16x32_bf16 v[58:61], v[78:81], v[14:17], v[58:61]
	ds_read_b128 v[78:81], v131 offset:54272
	v_max3_f32 v195, v160, v161, v162
	v_max3_f32 v195, v195, v163, v164
	v_max3_f32 v195, v195, v165, v166
	v_max_f32_e32 v195, v195, v167
	ds_read_b128 v[82:85], v131 offset:63488
	s_waitcnt lgkmcnt(3)
	v_mfma_f32_16x16x32_bf16 v[54:57], v[86:89], v[14:17], v[54:57]
	ds_read_b128 v[86:89], v131 offset:56320
	v_readlane_b32 s51, v255, 8
	s_nop 1
	s_cmpk_ge_u32 s51, 0x100
	s_cbranch_scc1 .Latt_stgA_skip_1
	s_cmp_ge_u32 s73, s71
	s_cbranch_scc1 .Latt_stgA_skip_1
	s_mul_hi_u32 s49, s50, 0xaaaaaaab
	s_lshr_b32 s49, s49, 1
	s_mul_i32 s49, s49, 0xc000
	s_sub_i32 s49, s31, s49
	s_add_i32 s49, s36, s49
	s_add_i32 s49, s2, s49
	s_lshl_b32 s51, s37, 14
	s_add_i32 s51, s76, s51
	s_mov_b32 m0, s49
	s_add_i32 s50, s51, 0xc000
	global_load_lds_dwordx4 v[114:115], off
	v_lshl_add_u64 v[192:193], v[114:115], 0, s[44:45]
	s_add_i32 m0, s49, 0x2000
	s_nop 0
	global_load_lds_dwordx4 v[192:193], off
	s_mov_b32 m0, s50
	s_nop 0
	global_load_lds_dwordx4 v[118:119], off
	s_add_i32 m0, s51, 0xe000
	s_nop 0
	global_load_lds_dwordx4 v[116:117], off
.Latt_stgA_skip_1:
	ds_read_b128 v[90:93], v131 offset:50176
	s_waitcnt lgkmcnt(4)
	v_mfma_f32_16x16x32_bf16 v[46:49], v[176:179], v[14:17], v[46:49]
	ds_read_b128 v[176:179], v131 offset:58368
	v_exp_f32_e32 v98, v70
	v_exp_f32_e32 v99, v71
	v_exp_f32_e32 v100, v72
	v_exp_f32_e32 v101, v73
	ds_read_b128 v[180:183], v131 offset:52224
	s_waitcnt lgkmcnt(4)
	v_mfma_f32_16x16x32_bf16 v[38:41], v[82:85], v[14:17], v[38:41]
	v_max3_f32 v194, v168, v169, v170
	v_max3_f32 v194, v194, v171, v172
	v_max3_f32 v194, v194, v173, v174
	v_max3_f32 v194, v194, v175, v195
	v_mfma_f32_16x16x32_bf16 v[2:5], v[154:157], v[14:17], v[2:5]
	v_exp_f32_e32 v102, v22
	v_exp_f32_e32 v103, v23
	v_exp_f32_e32 v104, v24
	v_exp_f32_e32 v105, v25
	ds_read_b128 v[94:97], v131 offset:60416
	s_waitcnt lgkmcnt(3)
	v_mfma_f32_16x16x32_bf16 v[30:33], v[90:93], v[6:9], v[30:33]
	ds_read_b128 v[90:93], v131 offset:62464
	v_readlane_b32 s51, v255, 8
	s_nop 1
	s_cmpk_lt_u32 s51, 0x100
	s_cbranch_scc1 .Latt_stgA_skip_2
	s_cmp_ge_u32 s73, s71
	s_cbranch_scc1 .Latt_stgA_skip_2
	s_mul_hi_u32 s49, s50, 0xaaaaaaab
	s_lshr_b32 s49, s49, 1
	s_mul_i32 s49, s49, 0xc000
	s_sub_i32 s49, s31, s49
	s_add_i32 s49, s36, s49
	s_add_i32 s49, s2, s49
	s_lshl_b32 s51, s37, 14
	s_add_i32 s51, s76, s51
	s_mov_b32 m0, s49
	s_add_i32 s50, s51, 0xc000
	global_load_lds_dwordx4 v[114:115], off
	v_lshl_add_u64 v[192:193], v[114:115], 0, s[44:45]
	s_add_i32 m0, s49, 0x2000
	s_nop 0
	global_load_lds_dwordx4 v[192:193], off
	s_mov_b32 m0, s50
	s_nop 0
	global_load_lds_dwordx4 v[118:119], off
	s_add_i32 m0, s51, 0xe000
	s_nop 0
	global_load_lds_dwordx4 v[116:117], off
.Latt_stgA_skip_2:
	v_mov_b32_e32 v158, v194
	s_nop 1
	v_permlane16_swap_b32_e32 v194, v158
	v_max_f32_e32 v194, v194, v158
	s_waitcnt lgkmcnt(2)
	v_mfma_f32_16x16x32_bf16 v[50:53], v[180:183], v[6:9], v[50:53]
	ds_read_b128 v[180:183], v131 offset:64512
	v_exp_f32_e32 v133, v26
	v_exp_f32_e32 v134, v27
	v_exp_f32_e32 v135, v28
	v_exp_f32_e32 v136, v29
	v_mfma_f32_16x16x32_bf16 v[42:45], v[78:81], v[6:9], v[42:45]
	v_mov_b32_e32 v158, v194
	s_nop 1
	v_permlane32_swap_b32_e32 v194, v158
	v_max_f32_e32 v194, v194, v158
	v_mfma_f32_16x16x32_bf16 v[34:37], v[86:89], v[6:9], v[34:37]
	v_cvt_pk_bf16_f32 v14, v145, v146
	v_cvt_pk_bf16_f32 v15, v147, v148
	v_cvt_pk_bf16_f32 v16, v98, v99
	v_cvt_pk_bf16_f32 v17, v100, v101
	v_cvt_pk_bf16_f32 v184, v102, v103
	v_cvt_pk_bf16_f32 v185, v104, v105
	v_cvt_pk_bf16_f32 v186, v133, v134
	v_cvt_pk_bf16_f32 v187, v135, v136
	v_mfma_f32_16x16x32_bf16 v[58:61], v[176:179], v[6:9], v[58:61]
	s_waitcnt lgkmcnt(2)
	v_mfma_f32_16x16x32_bf16 v[54:57], v[94:97], v[6:9], v[54:57]
	s_waitcnt lgkmcnt(1)
	v_mfma_f32_16x16x32_bf16 v[46:49], v[90:93], v[6:9], v[46:49]
	s_waitcnt lgkmcnt(0)
	v_mfma_f32_16x16x32_bf16 v[38:41], v[180:183], v[6:9], v[38:41]
	v_mfma_f32_16x16x32_bf16 v[2:5], v[154:157], v[6:9], v[2:5]
	s_andn2_b64 vcc, exec, s[34:35]
	s_cbranch_vccnz .LBB0_1331
	v_sub_f32_e32 v160, v160, v132
	v_sub_f32_e32 v161, v161, v132
	v_sub_f32_e32 v162, v162, v132
	v_sub_f32_e32 v163, v163, v132
	v_sub_f32_e32 v164, v164, v132
	v_sub_f32_e32 v165, v165, v132
	v_sub_f32_e32 v166, v166, v132
	v_sub_f32_e32 v167, v167, v132
	v_sub_f32_e32 v168, v168, v132
	v_sub_f32_e32 v169, v169, v132
	v_sub_f32_e32 v170, v170, v132
	v_sub_f32_e32 v171, v171, v132
	v_sub_f32_e32 v172, v172, v132
	v_sub_f32_e32 v173, v173, v132
	v_sub_f32_e32 v174, v174, v132
	v_sub_f32_e32 v175, v175, v132
	v_sub_f32_e32 v194, v194, v132
	v_pk_mul_f32 v[40:41], v[0:1], v[40:41] op_sel_hi:[0,1]
	v_pk_mul_f32 v[48:49], v[0:1], v[48:49] op_sel_hi:[0,1]
	v_pk_mul_f32 v[56:57], v[0:1], v[56:57] op_sel_hi:[0,1]
	v_pk_mul_f32 v[60:61], v[0:1], v[60:61] op_sel_hi:[0,1]
	v_pk_mul_f32 v[36:37], v[0:1], v[36:37] op_sel_hi:[0,1]
	v_pk_mul_f32 v[44:45], v[0:1], v[44:45] op_sel_hi:[0,1]
	v_pk_mul_f32 v[52:53], v[0:1], v[52:53] op_sel_hi:[0,1]
	v_pk_mul_f32 v[32:33], v[0:1], v[32:33] op_sel_hi:[0,1]
	v_pk_mul_f32 v[38:39], v[0:1], v[38:39] op_sel_hi:[0,1]
	v_pk_mul_f32 v[46:47], v[0:1], v[46:47] op_sel_hi:[0,1]
	v_pk_mul_f32 v[54:55], v[0:1], v[54:55] op_sel_hi:[0,1]
	v_pk_mul_f32 v[58:59], v[0:1], v[58:59] op_sel_hi:[0,1]
	v_pk_mul_f32 v[34:35], v[0:1], v[34:35] op_sel_hi:[0,1]
	v_pk_mul_f32 v[42:43], v[0:1], v[42:43] op_sel_hi:[0,1]
	v_pk_mul_f32 v[50:51], v[0:1], v[50:51] op_sel_hi:[0,1]
	v_pk_mul_f32 v[30:31], v[0:1], v[30:31] op_sel_hi:[0,1]
	v_pk_mul_f32 v[4:5], v[0:1], v[4:5] op_sel_hi:[0,1]
	v_pk_mul_f32 v[2:3], v[0:1], v[2:3] op_sel_hi:[0,1]

.Latt_B_1328:
.Latt_B_1329:
	s_waitcnt lgkmcnt(1)
	v_mfma_f32_16x16x32_bf16 v[22:25], v[78:81], v[18:21], v[90:93]
	ds_read_b128 v[78:81], v131 offset:57344
	s_waitcnt lgkmcnt(1)
	v_mfma_f32_16x16x32_bf16 v[26:29], v[86:89], v[18:21], v[94:97]
	ds_read_b128 v[86:89], v131 offset:59392
	v_exp_f32_e32 v145, v160
	v_exp_f32_e32 v146, v161
	v_exp_f32_e32 v147, v162
	v_exp_f32_e32 v148, v163
	ds_read_b128 v[176:179], v131 offset:61440
	s_waitcnt lgkmcnt(2)
	v_mfma_f32_16x16x32_bf16 v[58:61], v[78:81], v[14:17], v[58:61]
	ds_read_b128 v[78:81], v131 offset:54272
	v_max3_f32 v195, v74, v75, v76
	v_max3_f32 v195, v195, v77, v70
	v_max3_f32 v195, v195, v71, v72
	v_max_f32_e32 v195, v195, v73
	ds_read_b128 v[82:85], v131 offset:63488
	s_waitcnt lgkmcnt(3)
	v_mfma_f32_16x16x32_bf16 v[54:57], v[86:89], v[14:17], v[54:57]
	ds_read_b128 v[86:89], v131 offset:56320
	v_readlane_b32 s51, v255, 8
	s_nop 1
	s_cmpk_ge_u32 s51, 0x100
	s_cbranch_scc1 .Latt_stgB_skip_1
	s_cmp_ge_u32 s73, s71
	s_cbranch_scc1 .Latt_stgB_skip_1
	s_mul_hi_u32 s49, s50, 0xaaaaaaab
	s_lshr_b32 s49, s49, 1
	s_mul_i32 s49, s49, 0xc000
	s_sub_i32 s49, s31, s49
	s_add_i32 s49, s36, s49
	s_add_i32 s49, s2, s49
	s_lshl_b32 s51, s37, 14
	s_add_i32 s51, s76, s51
	s_mov_b32 m0, s49
	s_add_i32 s50, s51, 0xc000
	global_load_lds_dwordx4 v[114:115], off
	v_lshl_add_u64 v[192:193], v[114:115], 0, s[44:45]
	s_add_i32 m0, s49, 0x2000
	s_nop 0
	global_load_lds_dwordx4 v[192:193], off
	s_mov_b32 m0, s50
	s_nop 0
	global_load_lds_dwordx4 v[118:119], off
	s_add_i32 m0, s51, 0xe000
	s_nop 0
	global_load_lds_dwordx4 v[116:117], off
.Latt_stgB_skip_1:
	ds_read_b128 v[90:93], v131 offset:50176
	s_waitcnt lgkmcnt(4)
	v_mfma_f32_16x16x32_bf16 v[46:49], v[176:179], v[14:17], v[46:49]
	ds_read_b128 v[176:179], v131 offset:58368
	v_exp_f32_e32 v98, v164
	v_exp_f32_e32 v99, v165
	v_exp_f32_e32 v100, v166
	v_exp_f32_e32 v101, v167
	ds_read_b128 v[180:183], v131 offset:52224
	s_waitcnt lgkmcnt(4)
	v_mfma_f32_16x16x32_bf16 v[38:41], v[82:85], v[14:17], v[38:41]
	v_max3_f32 v194, v22, v23, v24
	v_max3_f32 v194, v194, v25, v26
	v_max3_f32 v194, v194, v27, v28
	v_max3_f32 v194, v194, v29, v195
	v_mfma_f32_16x16x32_bf16 v[2:5], v[154:157], v[14:17], v[2:5]
	v_exp_f32_e32 v102, v168
	v_exp_f32_e32 v103, v169
	v_exp_f32_e32 v104, v170
	v_exp_f32_e32 v105, v171
	ds_read_b128 v[94:97], v131 offset:60416
	s_waitcnt lgkmcnt(3)
	v_mfma_f32_16x16x32_bf16 v[30:33], v[90:93], v[184:187], v[30:33]
	ds_read_b128 v[90:93], v131 offset:62464
	v_readlane_b32 s51, v255, 8
	s_nop 1
	s_cmpk_lt_u32 s51, 0x100
	s_cbranch_scc1 .Latt_stgB_skip_2
	s_cmp_ge_u32 s73, s71
	s_cbranch_scc1 .Latt_stgB_skip_2
	s_mul_hi_u32 s49, s50, 0xaaaaaaab
	s_lshr_b32 s49, s49, 1
	s_mul_i32 s49, s49, 0xc000
	s_sub_i32 s49, s31, s49
	s_add_i32 s49, s36, s49
	s_add_i32 s49, s2, s49
	s_lshl_b32 s51, s37, 14
	s_add_i32 s51, s76, s51
	s_mov_b32 m0, s49
	s_add_i32 s50, s51, 0xc000
	global_load_lds_dwordx4 v[114:115], off
	v_lshl_add_u64 v[192:193], v[114:115], 0, s[44:45]
	s_add_i32 m0, s49, 0x2000
	s_nop 0
	global_load_lds_dwordx4 v[192:193], off
	s_mov_b32 m0, s50
	s_nop 0
	global_load_lds_dwordx4 v[118:119], off
	s_add_i32 m0, s51, 0xe000
	s_nop 0
	global_load_lds_dwordx4 v[116:117], off
.Latt_stgB_skip_2:
	v_mov_b32_e32 v158, v194
	s_nop 1
	v_permlane16_swap_b32_e32 v194, v158
	v_max_f32_e32 v194, v194, v158
	s_waitcnt lgkmcnt(2)
	v_mfma_f32_16x16x32_bf16 v[50:53], v[180:183], v[184:187], v[50:53]
	ds_read_b128 v[180:183], v131 offset:64512
	v_exp_f32_e32 v133, v172
	v_exp_f32_e32 v134, v173
	v_exp_f32_e32 v135, v174
	v_exp_f32_e32 v136, v175
	v_mfma_f32_16x16x32_bf16 v[42:45], v[78:81], v[184:187], v[42:45]
	v_mov_b32_e32 v158, v194
	s_nop 1
	v_permlane32_swap_b32_e32 v194, v158
	v_max_f32_e32 v194, v194, v158
	v_mfma_f32_16x16x32_bf16 v[34:37], v[86:89], v[184:187], v[34:37]
	v_cvt_pk_bf16_f32 v14, v145, v146
	v_cvt_pk_bf16_f32 v15, v147, v148
	v_cvt_pk_bf16_f32 v16, v98, v99
	v_cvt_pk_bf16_f32 v17, v100, v101
	v_cvt_pk_bf16_f32 v6, v102, v103
	v_cvt_pk_bf16_f32 v7, v104, v105
	v_cvt_pk_bf16_f32 v8, v133, v134
	v_cvt_pk_bf16_f32 v9, v135, v136
	v_mfma_f32_16x16x32_bf16 v[58:61], v[176:179], v[184:187], v[58:61]
	s_waitcnt lgkmcnt(2)
	v_mfma_f32_16x16x32_bf16 v[54:57], v[94:97], v[184:187], v[54:57]
	s_waitcnt lgkmcnt(1)
	v_mfma_f32_16x16x32_bf16 v[46:49], v[90:93], v[184:187], v[46:49]
	s_waitcnt lgkmcnt(0)
	v_mfma_f32_16x16x32_bf16 v[38:41], v[180:183], v[184:187], v[38:41]
	v_mfma_f32_16x16x32_bf16 v[2:5], v[154:157], v[184:187], v[2:5]
	s_andn2_b64 vcc, exec, s[34:35]
	s_cbranch_vccnz .Latt_B_1331
	v_sub_f32_e32 v74, v74, v132
	v_sub_f32_e32 v75, v75, v132
	v_sub_f32_e32 v76, v76, v132
	v_sub_f32_e32 v77, v77, v132
	v_sub_f32_e32 v70, v70, v132
	v_sub_f32_e32 v71, v71, v132
	v_sub_f32_e32 v72, v72, v132
	v_sub_f32_e32 v73, v73, v132
	v_sub_f32_e32 v22, v22, v132
	v_sub_f32_e32 v23, v23, v132
	v_sub_f32_e32 v24, v24, v132
	v_sub_f32_e32 v25, v25, v132
	v_sub_f32_e32 v26, v26, v132
	v_sub_f32_e32 v27, v27, v132
	v_sub_f32_e32 v28, v28, v132
	v_sub_f32_e32 v29, v29, v132
	v_sub_f32_e32 v194, v194, v132
	v_pk_mul_f32 v[40:41], v[0:1], v[40:41] op_sel_hi:[0,1]
	v_pk_mul_f32 v[48:49], v[0:1], v[48:49] op_sel_hi:[0,1]
	v_pk_mul_f32 v[56:57], v[0:1], v[56:57] op_sel_hi:[0,1]
	v_pk_mul_f32 v[60:61], v[0:1], v[60:61] op_sel_hi:[0,1]
	v_pk_mul_f32 v[36:37], v[0:1], v[36:37] op_sel_hi:[0,1]
	v_pk_mul_f32 v[44:45], v[0:1], v[44:45] op_sel_hi:[0,1]
	v_pk_mul_f32 v[52:53], v[0:1], v[52:53] op_sel_hi:[0,1]
	v_pk_mul_f32 v[32:33], v[0:1], v[32:33] op_sel_hi:[0,1]
	v_pk_mul_f32 v[38:39], v[0:1], v[38:39] op_sel_hi:[0,1]
	v_pk_mul_f32 v[46:47], v[0:1], v[46:47] op_sel_hi:[0,1]
	v_pk_mul_f32 v[54:55], v[0:1], v[54:55] op_sel_hi:[0,1]
	v_pk_mul_f32 v[58:59], v[0:1], v[58:59] op_sel_hi:[0,1]
	v_pk_mul_f32 v[34:35], v[0:1], v[34:35] op_sel_hi:[0,1]
	v_pk_mul_f32 v[42:43], v[0:1], v[42:43] op_sel_hi:[0,1]
	v_pk_mul_f32 v[50:51], v[0:1], v[50:51] op_sel_hi:[0,1]
	v_pk_mul_f32 v[30:31], v[0:1], v[30:31] op_sel_hi:[0,1]
	v_pk_mul_f32 v[4:5], v[0:1], v[4:5] op_sel_hi:[0,1]
	v_pk_mul_f32 v[2:3], v[0:1], v[2:3] op_sel_hi:[0,1]
